# v62 with EpiAct transcendental ops (v_exp/v_rcp) interleaved with the packed f32 muls/adds instead of issued in runs of 8
# speedup vs baseline: 1.0007x; 1.0007x over previous
; __device__ __forceinline__ unsigned cvt_pk_bf16(float lo, float hi) { unsigned r; asm volatile("v_cvt_pk_bf16_f32 %0, %1, %2" : "=v"(r) : "v"(lo), "v"(hi)); return r; }
; #define LAS __attribute__((address_space(3)))
; __device__ __forceinline__ float siluf_(float x) { return x * __builtin_amdgcn_rcpf(1.0f + __builtin_amdgcn_exp2f(-1.4426950408889634f * x)); }
; __device__ __forceinline__ float rstd_of(float ss) { return __builtin_amdgcn_rsqf(ss * (1.0f / DM) + EPS); }
;     __device__ __forceinline__ void operator()(const pg8::f32x4 (&acc)[2][2][4][2], const Unit& u, int wr, int wc, int fr, int fq) const {
;         const int row0 = u.pm * BM + wr * 64, lane = fr + 16 * fq, rr = lane >> 2, sl = lane & 3;
;         LAS unsigned char* W = scr + (wr * 4 + wc) * 2048;
;         bf16* outp = ACT + (size_t)(row0 + rr) * DFF + u.pn * HALF + wc * 32 + sl * 8;
; #pragma unroll
;         for (int ai = 0; ai < 2; ++ai)
; #pragma unroll
;             for (int m = 0; m < 4; ++m) { const int rg = ai * HALF + m * 16; const float rs = rstd_of(SS1[row0 + rg + fr]);
;                 const pg8::f32x4 g0 = acc[ai][0][m][0] * rs, g1 = acc[ai][0][m][1] * rs, u0 = acc[ai][1][m][0] * rs, u1 = acc[ai][1][m][1] * rs;
;                 u32x4 w; w.x = cvt_pk_bf16(siluf_(g0[0]) * u0[0], siluf_(g0[1]) * u0[1]); w.y = cvt_pk_bf16(siluf_(g0[2]) * u0[2], siluf_(g0[3]) * u0[3]);
;                 w.z = cvt_pk_bf16(siluf_(g1[0]) * u1[0], siluf_(g1[1]) * u1[1]); w.w = cvt_pk_bf16(siluf_(g1[2]) * u1[2], siluf_(g1[3]) * u1[3]);
;                 *(LAS u32x4*)epi_slot(W, fr, fq + 4 * (m & 1)) = w;
;                 const u32x4 o = *(const LAS u32x4*)epi_slot(W, rr, sl + 4 * (m & 1));
;                 *(u32x4*)(outp + (size_t)rg * DFF) = o; }
.LBB0_880:
	s_lshl_b32 s4, s4, 8
	s_add_i32 s21, s4, s42
	v_or_b32_e32 v148, s21, v152
	v_ashrrev_i32_e32 v149, 31, v148
	v_lshl_add_u64 v[150:151], v[148:149], 2, s[14:15]
	v_lshlrev_b32_e32 v208, 2, v152
	v_add_u32_e32 v209, 64, v208
	v_add_u32_e32 v210, 0x80, v208
	v_add_u32_e32 v211, 0xc0, v208
	ds_bpermute_b32 v200, v208, v234
	ds_bpermute_b32 v201, v209, v234
	ds_bpermute_b32 v202, v210, v234
	ds_bpermute_b32 v203, v211, v234
	ds_bpermute_b32 v204, v208, v235
	ds_bpermute_b32 v205, v209, v235
	ds_bpermute_b32 v206, v210, v235
	ds_bpermute_b32 v207, v211, v235
	v_mov_b32_e32 v212, 0xbfb8aa3b
	v_mov_b32_e32 v214, 1.0
	v_mov_b64_e32 v[164:165], s[56:57]
	s_lshl_b32 s4, s5, 7
	s_ashr_i32 s5, s4, 31
	s_waitcnt lgkmcnt(0)
	v_fmamk_f32 v149, v200, 0x3a800000, v159
	v_rsq_f32_e32 v166, v149
	v_or_b32_e32 v149, s21, v153
	v_pk_mul_f32 v[124:125], v[124:125], v[166:167] op_sel_hi:[1,0]
	v_pk_mul_f32 v[128:129], v[128:129], v[166:167] op_sel_hi:[1,0]
	v_pk_mul_f32 v[126:127], v[126:127], v[166:167] op_sel_hi:[1,0]
	v_pk_mul_f32 v[122:123], v[122:123], v[166:167] op_sel_hi:[1,0]
	v_pk_mul_f32 v[120:121], v[120:121], v[166:167] op_sel_hi:[1,0]
	v_pk_mul_f32 v[118:119], v[118:119], v[166:167] op_sel_hi:[1,0]
	v_pk_mul_f32 v[116:117], v[116:117], v[166:167] op_sel_hi:[1,0]
	v_pk_mul_f32 v[114:115], v[114:115], v[166:167] op_sel_hi:[1,0]
	v_pk_mul_f32 v[216:217], v[122:123], v[212:213] op_sel_hi:[1,0]
	v_pk_mul_f32 v[218:219], v[124:125], v[212:213] op_sel_hi:[1,0]
	v_pk_mul_f32 v[220:221], v[126:127], v[212:213] op_sel_hi:[1,0]
	v_pk_mul_f32 v[222:223], v[128:129], v[212:213] op_sel_hi:[1,0]
	v_exp_f32_e32 v216, v216
	v_exp_f32_e32 v217, v217
	v_exp_f32_e32 v218, v218
	v_exp_f32_e32 v219, v219
	v_exp_f32_e32 v220, v220
	v_pk_add_f32 v[216:217], v[216:217], v[214:215] op_sel_hi:[1,0]
	v_exp_f32_e32 v221, v221
	v_pk_add_f32 v[218:219], v[218:219], v[214:215] op_sel_hi:[1,0]
	v_exp_f32_e32 v222, v222
	v_exp_f32_e32 v223, v223
	v_rcp_f32_e32 v216, v216
	v_pk_add_f32 v[220:221], v[220:221], v[214:215] op_sel_hi:[1,0]
	v_rcp_f32_e32 v217, v217
	v_pk_add_f32 v[222:223], v[222:223], v[214:215] op_sel_hi:[1,0]
	v_rcp_f32_e32 v218, v218
	v_rcp_f32_e32 v219, v219
	v_rcp_f32_e32 v220, v220
	v_pk_mul_f32 v[122:123], v[122:123], v[216:217]
	v_rcp_f32_e32 v221, v221
	v_pk_mul_f32 v[122:123], v[114:115], v[122:123]
	v_rcp_f32_e32 v222, v222
	v_pk_mul_f32 v[124:125], v[124:125], v[218:219]
	v_rcp_f32_e32 v223, v223
	v_pk_mul_f32 v[116:117], v[116:117], v[124:125]
	v_pk_mul_f32 v[126:127], v[126:127], v[220:221]
	v_pk_mul_f32 v[118:119], v[118:119], v[126:127]
	v_pk_mul_f32 v[128:129], v[128:129], v[222:223]
	v_pk_mul_f32 v[120:121], v[120:121], v[128:129]
	v_cvt_pk_bf16_f32 v114, v118, v119
	v_cvt_pk_bf16_f32 v115, v120, v121
	v_cvt_pk_bf16_f32 v117, v116, v117
	v_cvt_pk_bf16_f32 v116, v122, v123
	ds_write_b128 v160, v[114:117]
	ds_read_b128 v[116:119], v161
	v_mad_i64_i32 v[114:115], s[28:29], v149, s55, v[164:165]
	v_lshl_add_u64 v[114:115], s[4:5], 1, v[114:115]
	v_lshl_add_u64 v[114:115], v[114:115], 0, s[6:7]
	v_lshl_add_u64 v[114:115], v[114:115], 0, v[138:139]
	s_waitcnt lgkmcnt(0)
	global_store_dwordx4 v[114:115], v[116:119], off
	s_nop 1
	v_fmamk_f32 v116, v201, 0x3a800000, v159
	v_rsq_f32_e32 v116, v116
	s_nop 0
	v_pk_mul_f32 v[108:109], v[108:109], v[116:117] op_sel_hi:[1,0]
	v_pk_mul_f32 v[112:113], v[112:113], v[116:117] op_sel_hi:[1,0]
	v_pk_mul_f32 v[110:111], v[110:111], v[116:117] op_sel_hi:[1,0]
	v_pk_mul_f32 v[106:107], v[106:107], v[116:117] op_sel_hi:[1,0]
	v_pk_mul_f32 v[104:105], v[104:105], v[116:117] op_sel_hi:[1,0]
	v_pk_mul_f32 v[102:103], v[102:103], v[116:117] op_sel_hi:[1,0]
	v_pk_mul_f32 v[100:101], v[100:101], v[116:117] op_sel_hi:[1,0]
	v_pk_mul_f32 v[98:99], v[98:99], v[116:117] op_sel_hi:[1,0]
	v_pk_mul_f32 v[216:217], v[106:107], v[212:213] op_sel_hi:[1,0]
	v_pk_mul_f32 v[218:219], v[108:109], v[212:213] op_sel_hi:[1,0]
	v_pk_mul_f32 v[220:221], v[110:111], v[212:213] op_sel_hi:[1,0]
	v_pk_mul_f32 v[222:223], v[112:113], v[212:213] op_sel_hi:[1,0]
	v_exp_f32_e32 v216, v216
	v_exp_f32_e32 v217, v217
	v_exp_f32_e32 v218, v218
	v_exp_f32_e32 v219, v219
	v_exp_f32_e32 v220, v220
	v_pk_add_f32 v[216:217], v[216:217], v[214:215] op_sel_hi:[1,0]
	v_exp_f32_e32 v221, v221
	v_pk_add_f32 v[218:219], v[218:219], v[214:215] op_sel_hi:[1,0]
	v_exp_f32_e32 v222, v222
	v_exp_f32_e32 v223, v223
	v_rcp_f32_e32 v216, v216
	v_pk_add_f32 v[220:221], v[220:221], v[214:215] op_sel_hi:[1,0]
	v_rcp_f32_e32 v217, v217
	v_pk_add_f32 v[222:223], v[222:223], v[214:215] op_sel_hi:[1,0]
	v_rcp_f32_e32 v218, v218
	v_rcp_f32_e32 v219, v219
	v_rcp_f32_e32 v220, v220
	v_pk_mul_f32 v[106:107], v[106:107], v[216:217]
	v_rcp_f32_e32 v221, v221
	v_pk_mul_f32 v[106:107], v[98:99], v[106:107]
	v_rcp_f32_e32 v222, v222
	v_pk_mul_f32 v[108:109], v[108:109], v[218:219]
	v_rcp_f32_e32 v223, v223
	v_pk_mul_f32 v[100:101], v[100:101], v[108:109]
	v_pk_mul_f32 v[110:111], v[110:111], v[220:221]
	v_pk_mul_f32 v[102:103], v[102:103], v[110:111]
	v_pk_mul_f32 v[112:113], v[112:113], v[222:223]
	v_pk_mul_f32 v[104:105], v[104:105], v[112:113]
	v_cvt_pk_bf16_f32 v98, v102, v103
	v_cvt_pk_bf16_f32 v99, v104, v105
	v_cvt_pk_bf16_f32 v101, v100, v101
	v_cvt_pk_bf16_f32 v100, v106, v107
	ds_write_b128 v162, v[98:101]
	ds_read_b128 v[98:101], v163
	v_add_co_u32_e32 v102, vcc, s41, v114
	s_nop 1
	v_addc_co_u32_e32 v103, vcc, 0, v115, vcc
	s_waitcnt lgkmcnt(0)
; __device__ __forceinline__ unsigned cvt_pk_bf16(float lo, float hi) { unsigned r; asm volatile("v_cvt_pk_bf16_f32 %0, %1, %2" : "=v"(r) : "v"(lo), "v"(hi)); return r; }
; #define LAS __attribute__((address_space(3)))
; __device__ __forceinline__ float siluf_(float x) { return x * __builtin_amdgcn_rcpf(1.0f + __builtin_amdgcn_exp2f(-1.4426950408889634f * x)); }
; __device__ __forceinline__ float rstd_of(float ss) { return __builtin_amdgcn_rsqf(ss * (1.0f / DM) + EPS); }
;     __device__ __forceinline__ void operator()(const pg8::f32x4 (&acc)[2][2][4][2], const Unit& u, int wr, int wc, int fr, int fq) const {
;         const int row0 = u.pm * BM + wr * 64, lane = fr + 16 * fq, rr = lane >> 2, sl = lane & 3;
;         LAS unsigned char* W = scr + (wr * 4 + wc) * 2048;
;         bf16* outp = ACT + (size_t)(row0 + rr) * DFF + u.pn * HALF + wc * 32 + sl * 8;
; #pragma unroll
;         for (int ai = 0; ai < 2; ++ai)
; #pragma unroll
;             for (int m = 0; m < 4; ++m) { const int rg = ai * HALF + m * 16; const float rs = rstd_of(SS1[row0 + rg + fr]);
;                 const pg8::f32x4 g0 = acc[ai][0][m][0] * rs, g1 = acc[ai][0][m][1] * rs, u0 = acc[ai][1][m][0] * rs, u1 = acc[ai][1][m][1] * rs;
;                 u32x4 w; w.x = cvt_pk_bf16(siluf_(g0[0]) * u0[0], siluf_(g0[1]) * u0[1]); w.y = cvt_pk_bf16(siluf_(g0[2]) * u0[2], siluf_(g0[3]) * u0[3]);
;                 w.z = cvt_pk_bf16(siluf_(g1[0]) * u1[0], siluf_(g1[1]) * u1[1]); w.w = cvt_pk_bf16(siluf_(g1[2]) * u1[2], siluf_(g1[3]) * u1[3]);
;                 *(LAS u32x4*)epi_slot(W, fr, fq + 4 * (m & 1)) = w;
;                 const u32x4 o = *(const LAS u32x4*)epi_slot(W, rr, sl + 4 * (m & 1));
;                 *(u32x4*)(outp + (size_t)rg * DFF) = o; }
	global_store_dwordx4 v[102:103], v[98:101], off
	s_nop 1
	v_fmamk_f32 v98, v202, 0x3a800000, v159
	v_rsq_f32_e32 v98, v98
	s_nop 0
	v_pk_mul_f32 v[92:93], v[92:93], v[98:99] op_sel_hi:[1,0]
	v_pk_mul_f32 v[96:97], v[96:97], v[98:99] op_sel_hi:[1,0]
	v_pk_mul_f32 v[94:95], v[94:95], v[98:99] op_sel_hi:[1,0]
	v_pk_mul_f32 v[90:91], v[90:91], v[98:99] op_sel_hi:[1,0]
	v_pk_mul_f32 v[88:89], v[88:89], v[98:99] op_sel_hi:[1,0]
	v_pk_mul_f32 v[86:87], v[86:87], v[98:99] op_sel_hi:[1,0]
	v_pk_mul_f32 v[84:85], v[84:85], v[98:99] op_sel_hi:[1,0]
	v_pk_mul_f32 v[82:83], v[82:83], v[98:99] op_sel_hi:[1,0]
	v_pk_mul_f32 v[216:217], v[90:91], v[212:213] op_sel_hi:[1,0]
	v_pk_mul_f32 v[218:219], v[92:93], v[212:213] op_sel_hi:[1,0]
	v_pk_mul_f32 v[220:221], v[94:95], v[212:213] op_sel_hi:[1,0]
	v_pk_mul_f32 v[222:223], v[96:97], v[212:213] op_sel_hi:[1,0]
	v_exp_f32_e32 v216, v216
	v_exp_f32_e32 v217, v217
	v_exp_f32_e32 v218, v218
	v_exp_f32_e32 v219, v219
	v_exp_f32_e32 v220, v220
	v_pk_add_f32 v[216:217], v[216:217], v[214:215] op_sel_hi:[1,0]
	v_exp_f32_e32 v221, v221
	v_pk_add_f32 v[218:219], v[218:219], v[214:215] op_sel_hi:[1,0]
	v_exp_f32_e32 v222, v222
	v_exp_f32_e32 v223, v223
	v_rcp_f32_e32 v216, v216
	v_pk_add_f32 v[220:221], v[220:221], v[214:215] op_sel_hi:[1,0]
	v_rcp_f32_e32 v217, v217
	v_pk_add_f32 v[222:223], v[222:223], v[214:215] op_sel_hi:[1,0]
	v_rcp_f32_e32 v218, v218
	v_rcp_f32_e32 v219, v219
	v_rcp_f32_e32 v220, v220
	v_pk_mul_f32 v[90:91], v[90:91], v[216:217]
	v_rcp_f32_e32 v221, v221
	v_pk_mul_f32 v[90:91], v[82:83], v[90:91]
	v_rcp_f32_e32 v222, v222
	v_pk_mul_f32 v[92:93], v[92:93], v[218:219]
	v_rcp_f32_e32 v223, v223
	v_pk_mul_f32 v[84:85], v[84:85], v[92:93]
	v_pk_mul_f32 v[94:95], v[94:95], v[220:221]
	v_pk_mul_f32 v[86:87], v[86:87], v[94:95]
	v_pk_mul_f32 v[96:97], v[96:97], v[222:223]
	v_pk_mul_f32 v[88:89], v[88:89], v[96:97]
	v_cvt_pk_bf16_f32 v82, v86, v87
	v_cvt_pk_bf16_f32 v83, v88, v89
	v_cvt_pk_bf16_f32 v85, v84, v85
	v_cvt_pk_bf16_f32 v84, v90, v91
	ds_write_b128 v160, v[82:85]
	ds_read_b128 v[82:85], v161
	v_add_co_u32_e32 v86, vcc, s58, v114
	s_nop 1
	v_addc_co_u32_e32 v87, vcc, 0, v115, vcc
	s_waitcnt lgkmcnt(0)
	global_store_dwordx4 v[86:87], v[82:85], off
	s_nop 1
	v_fmamk_f32 v82, v203, 0x3a800000, v159
	v_rsq_f32_e32 v82, v82
	s_nop 0
	v_pk_mul_f32 v[76:77], v[76:77], v[82:83] op_sel_hi:[1,0]
	v_pk_mul_f32 v[80:81], v[80:81], v[82:83] op_sel_hi:[1,0]
	v_pk_mul_f32 v[78:79], v[78:79], v[82:83] op_sel_hi:[1,0]
	v_pk_mul_f32 v[74:75], v[74:75], v[82:83] op_sel_hi:[1,0]
	v_pk_mul_f32 v[72:73], v[72:73], v[82:83] op_sel_hi:[1,0]
	v_pk_mul_f32 v[70:71], v[70:71], v[82:83] op_sel_hi:[1,0]
	v_pk_mul_f32 v[68:69], v[68:69], v[82:83] op_sel_hi:[1,0]
	v_pk_mul_f32 v[66:67], v[66:67], v[82:83] op_sel_hi:[1,0]
	v_pk_mul_f32 v[216:217], v[74:75], v[212:213] op_sel_hi:[1,0]
	v_pk_mul_f32 v[218:219], v[76:77], v[212:213] op_sel_hi:[1,0]
	v_pk_mul_f32 v[220:221], v[78:79], v[212:213] op_sel_hi:[1,0]
	v_pk_mul_f32 v[222:223], v[80:81], v[212:213] op_sel_hi:[1,0]
	v_exp_f32_e32 v216, v216
	v_exp_f32_e32 v217, v217
	v_exp_f32_e32 v218, v218
	v_exp_f32_e32 v219, v219
	v_exp_f32_e32 v220, v220
	v_pk_add_f32 v[216:217], v[216:217], v[214:215] op_sel_hi:[1,0]
	v_exp_f32_e32 v221, v221
	v_pk_add_f32 v[218:219], v[218:219], v[214:215] op_sel_hi:[1,0]
	v_exp_f32_e32 v222, v222
	v_exp_f32_e32 v223, v223
	v_rcp_f32_e32 v216, v216
	v_pk_add_f32 v[220:221], v[220:221], v[214:215] op_sel_hi:[1,0]
	v_rcp_f32_e32 v217, v217
	v_pk_add_f32 v[222:223], v[222:223], v[214:215] op_sel_hi:[1,0]
	v_rcp_f32_e32 v218, v218
	v_rcp_f32_e32 v219, v219
	v_rcp_f32_e32 v220, v220
	v_pk_mul_f32 v[74:75], v[74:75], v[216:217]
	v_rcp_f32_e32 v221, v221
	v_pk_mul_f32 v[74:75], v[66:67], v[74:75]
	v_rcp_f32_e32 v222, v222
	v_pk_mul_f32 v[76:77], v[76:77], v[218:219]
	v_rcp_f32_e32 v223, v223
	v_pk_mul_f32 v[68:69], v[68:69], v[76:77]
	v_pk_mul_f32 v[78:79], v[78:79], v[220:221]
	v_pk_mul_f32 v[70:71], v[70:71], v[78:79]
	v_pk_mul_f32 v[80:81], v[80:81], v[222:223]
	v_pk_mul_f32 v[72:73], v[72:73], v[80:81]
	v_cvt_pk_bf16_f32 v66, v70, v71
	v_cvt_pk_bf16_f32 v67, v72, v73
	v_cvt_pk_bf16_f32 v69, v68, v69
	v_cvt_pk_bf16_f32 v68, v74, v75
	ds_write_b128 v162, v[66:69]
	ds_read_b128 v[66:69], v163
	v_add_co_u32_e32 v70, vcc, s59, v114
	s_nop 1
	v_addc_co_u32_e32 v71, vcc, 0, v115, vcc
	s_waitcnt lgkmcnt(0)
	global_store_dwordx4 v[70:71], v[66:69], off
	s_nop 1
	v_fmamk_f32 v66, v204, 0x3a800000, v159
	v_rsq_f32_e32 v66, v66
	s_nop 0
	v_pk_mul_f32 v[60:61], v[60:61], v[66:67] op_sel_hi:[1,0]
	v_pk_mul_f32 v[64:65], v[64:65], v[66:67] op_sel_hi:[1,0]
	v_pk_mul_f32 v[62:63], v[62:63], v[66:67] op_sel_hi:[1,0]
	v_pk_mul_f32 v[58:59], v[58:59], v[66:67] op_sel_hi:[1,0]
	v_pk_mul_f32 v[56:57], v[56:57], v[66:67] op_sel_hi:[1,0]
	v_pk_mul_f32 v[54:55], v[54:55], v[66:67] op_sel_hi:[1,0]
	v_pk_mul_f32 v[52:53], v[52:53], v[66:67] op_sel_hi:[1,0]
	v_pk_mul_f32 v[50:51], v[50:51], v[66:67] op_sel_hi:[1,0]
	v_pk_mul_f32 v[216:217], v[58:59], v[212:213] op_sel_hi:[1,0]
	v_pk_mul_f32 v[218:219], v[60:61], v[212:213] op_sel_hi:[1,0]
	v_pk_mul_f32 v[220:221], v[62:63], v[212:213] op_sel_hi:[1,0]
	v_pk_mul_f32 v[222:223], v[64:65], v[212:213] op_sel_hi:[1,0]
	v_exp_f32_e32 v216, v216
	v_exp_f32_e32 v217, v217
	v_exp_f32_e32 v218, v218
	v_exp_f32_e32 v219, v219
	v_exp_f32_e32 v220, v220
	v_pk_add_f32 v[216:217], v[216:217], v[214:215] op_sel_hi:[1,0]
	v_exp_f32_e32 v221, v221
	v_pk_add_f32 v[218:219], v[218:219], v[214:215] op_sel_hi:[1,0]
	v_exp_f32_e32 v222, v222
	v_exp_f32_e32 v223, v223
	v_rcp_f32_e32 v216, v216
	v_pk_add_f32 v[220:221], v[220:221], v[214:215] op_sel_hi:[1,0]
	v_rcp_f32_e32 v217, v217
	v_pk_add_f32 v[222:223], v[222:223], v[214:215] op_sel_hi:[1,0]
	v_rcp_f32_e32 v218, v218
	v_rcp_f32_e32 v219, v219
	v_rcp_f32_e32 v220, v220
	v_pk_mul_f32 v[58:59], v[58:59], v[216:217]
	v_rcp_f32_e32 v221, v221
	v_pk_mul_f32 v[58:59], v[50:51], v[58:59]
	v_rcp_f32_e32 v222, v222
	v_pk_mul_f32 v[60:61], v[60:61], v[218:219]
	v_rcp_f32_e32 v223, v223
	v_pk_mul_f32 v[52:53], v[52:53], v[60:61]
	v_pk_mul_f32 v[62:63], v[62:63], v[220:221]
	v_pk_mul_f32 v[54:55], v[54:55], v[62:63]
	v_pk_mul_f32 v[64:65], v[64:65], v[222:223]
	v_pk_mul_f32 v[56:57], v[56:57], v[64:65]
	v_cvt_pk_bf16_f32 v50, v54, v55
	v_cvt_pk_bf16_f32 v51, v56, v57
	v_cvt_pk_bf16_f32 v53, v52, v53
	v_cvt_pk_bf16_f32 v52, v58, v59
	ds_write_b128 v160, v[50:53]
	ds_read_b128 v[50:53], v161
	v_add_co_u32_e32 v54, vcc, s60, v114
	s_nop 1
	v_addc_co_u32_e32 v55, vcc, 0, v115, vcc
	s_waitcnt lgkmcnt(0)
; __device__ __forceinline__ unsigned cvt_pk_bf16(float lo, float hi) { unsigned r; asm volatile("v_cvt_pk_bf16_f32 %0, %1, %2" : "=v"(r) : "v"(lo), "v"(hi)); return r; }
; #define LAS __attribute__((address_space(3)))
; __device__ __forceinline__ float siluf_(float x) { return x * __builtin_amdgcn_rcpf(1.0f + __builtin_amdgcn_exp2f(-1.4426950408889634f * x)); }
; __device__ __forceinline__ float rstd_of(float ss) { return __builtin_amdgcn_rsqf(ss * (1.0f / DM) + EPS); }
;     __device__ __forceinline__ void operator()(const pg8::f32x4 (&acc)[2][2][4][2], const Unit& u, int wr, int wc, int fr, int fq) const {
;         const int row0 = u.pm * BM + wr * 64, lane = fr + 16 * fq, rr = lane >> 2, sl = lane & 3;
;         LAS unsigned char* W = scr + (wr * 4 + wc) * 2048;
;         bf16* outp = ACT + (size_t)(row0 + rr) * DFF + u.pn * HALF + wc * 32 + sl * 8;
; #pragma unroll
;         for (int ai = 0; ai < 2; ++ai)
; #pragma unroll
;             for (int m = 0; m < 4; ++m) { const int rg = ai * HALF + m * 16; const float rs = rstd_of(SS1[row0 + rg + fr]);
;                 const pg8::f32x4 g0 = acc[ai][0][m][0] * rs, g1 = acc[ai][0][m][1] * rs, u0 = acc[ai][1][m][0] * rs, u1 = acc[ai][1][m][1] * rs;
;                 u32x4 w; w.x = cvt_pk_bf16(siluf_(g0[0]) * u0[0], siluf_(g0[1]) * u0[1]); w.y = cvt_pk_bf16(siluf_(g0[2]) * u0[2], siluf_(g0[3]) * u0[3]);
;                 w.z = cvt_pk_bf16(siluf_(g1[0]) * u1[0], siluf_(g1[1]) * u1[1]); w.w = cvt_pk_bf16(siluf_(g1[2]) * u1[2], siluf_(g1[3]) * u1[3]);
;                 *(LAS u32x4*)epi_slot(W, fr, fq + 4 * (m & 1)) = w;
;                 const u32x4 o = *(const LAS u32x4*)epi_slot(W, rr, sl + 4 * (m & 1));
;                 *(u32x4*)(outp + (size_t)rg * DFF) = o; }
	global_store_dwordx4 v[54:55], v[50:53], off
	s_nop 1
	v_fmamk_f32 v50, v205, 0x3a800000, v159
	v_rsq_f32_e32 v50, v50
	s_nop 0
	v_pk_mul_f32 v[44:45], v[44:45], v[50:51] op_sel_hi:[1,0]
	v_pk_mul_f32 v[48:49], v[48:49], v[50:51] op_sel_hi:[1,0]
	v_pk_mul_f32 v[46:47], v[46:47], v[50:51] op_sel_hi:[1,0]
	v_pk_mul_f32 v[42:43], v[42:43], v[50:51] op_sel_hi:[1,0]
	v_pk_mul_f32 v[40:41], v[40:41], v[50:51] op_sel_hi:[1,0]
	v_pk_mul_f32 v[38:39], v[38:39], v[50:51] op_sel_hi:[1,0]
	v_pk_mul_f32 v[36:37], v[36:37], v[50:51] op_sel_hi:[1,0]
	v_pk_mul_f32 v[34:35], v[34:35], v[50:51] op_sel_hi:[1,0]
	v_pk_mul_f32 v[216:217], v[42:43], v[212:213] op_sel_hi:[1,0]
	v_pk_mul_f32 v[218:219], v[44:45], v[212:213] op_sel_hi:[1,0]
	v_pk_mul_f32 v[220:221], v[46:47], v[212:213] op_sel_hi:[1,0]
	v_pk_mul_f32 v[222:223], v[48:49], v[212:213] op_sel_hi:[1,0]
	v_exp_f32_e32 v216, v216
	v_exp_f32_e32 v217, v217
	v_exp_f32_e32 v218, v218
	v_exp_f32_e32 v219, v219
	v_exp_f32_e32 v220, v220
	v_pk_add_f32 v[216:217], v[216:217], v[214:215] op_sel_hi:[1,0]
	v_exp_f32_e32 v221, v221
	v_pk_add_f32 v[218:219], v[218:219], v[214:215] op_sel_hi:[1,0]
	v_exp_f32_e32 v222, v222
	v_exp_f32_e32 v223, v223
	v_rcp_f32_e32 v216, v216
	v_pk_add_f32 v[220:221], v[220:221], v[214:215] op_sel_hi:[1,0]
	v_rcp_f32_e32 v217, v217
	v_pk_add_f32 v[222:223], v[222:223], v[214:215] op_sel_hi:[1,0]
	v_rcp_f32_e32 v218, v218
	v_rcp_f32_e32 v219, v219
	v_rcp_f32_e32 v220, v220
	v_pk_mul_f32 v[42:43], v[42:43], v[216:217]
	v_rcp_f32_e32 v221, v221
	v_pk_mul_f32 v[42:43], v[34:35], v[42:43]
	v_rcp_f32_e32 v222, v222
	v_pk_mul_f32 v[44:45], v[44:45], v[218:219]
	v_rcp_f32_e32 v223, v223
	v_pk_mul_f32 v[36:37], v[36:37], v[44:45]
	v_pk_mul_f32 v[46:47], v[46:47], v[220:221]
	v_pk_mul_f32 v[38:39], v[38:39], v[46:47]
	v_pk_mul_f32 v[48:49], v[48:49], v[222:223]
	v_pk_mul_f32 v[40:41], v[40:41], v[48:49]
	v_cvt_pk_bf16_f32 v34, v38, v39
	v_cvt_pk_bf16_f32 v35, v40, v41
	v_cvt_pk_bf16_f32 v37, v36, v37
	v_cvt_pk_bf16_f32 v36, v42, v43
	ds_write_b128 v162, v[34:37]
	ds_read_b128 v[34:37], v163
	v_add_co_u32_e32 v38, vcc, s61, v114
	s_nop 1
	v_addc_co_u32_e32 v39, vcc, 0, v115, vcc
	s_waitcnt lgkmcnt(0)
	global_store_dwordx4 v[38:39], v[34:37], off
	s_nop 1
	v_fmamk_f32 v34, v206, 0x3a800000, v159
	v_rsq_f32_e32 v34, v34
	s_nop 0
	v_pk_mul_f32 v[28:29], v[28:29], v[34:35] op_sel_hi:[1,0]
	v_pk_mul_f32 v[32:33], v[32:33], v[34:35] op_sel_hi:[1,0]
	v_pk_mul_f32 v[30:31], v[30:31], v[34:35] op_sel_hi:[1,0]
	v_pk_mul_f32 v[26:27], v[26:27], v[34:35] op_sel_hi:[1,0]
	v_pk_mul_f32 v[24:25], v[24:25], v[34:35] op_sel_hi:[1,0]
	v_pk_mul_f32 v[22:23], v[22:23], v[34:35] op_sel_hi:[1,0]
	v_pk_mul_f32 v[20:21], v[20:21], v[34:35] op_sel_hi:[1,0]
	v_pk_mul_f32 v[18:19], v[18:19], v[34:35] op_sel_hi:[1,0]
	v_pk_mul_f32 v[216:217], v[26:27], v[212:213] op_sel_hi:[1,0]
	v_pk_mul_f32 v[218:219], v[28:29], v[212:213] op_sel_hi:[1,0]
	v_pk_mul_f32 v[220:221], v[30:31], v[212:213] op_sel_hi:[1,0]
	v_pk_mul_f32 v[222:223], v[32:33], v[212:213] op_sel_hi:[1,0]
	v_exp_f32_e32 v216, v216
	v_exp_f32_e32 v217, v217
	v_exp_f32_e32 v218, v218
	v_exp_f32_e32 v219, v219
	v_exp_f32_e32 v220, v220
	v_pk_add_f32 v[216:217], v[216:217], v[214:215] op_sel_hi:[1,0]
	v_exp_f32_e32 v221, v221
	v_pk_add_f32 v[218:219], v[218:219], v[214:215] op_sel_hi:[1,0]
	v_exp_f32_e32 v222, v222
	v_exp_f32_e32 v223, v223
	v_rcp_f32_e32 v216, v216
	v_pk_add_f32 v[220:221], v[220:221], v[214:215] op_sel_hi:[1,0]
	v_rcp_f32_e32 v217, v217
	v_pk_add_f32 v[222:223], v[222:223], v[214:215] op_sel_hi:[1,0]
	v_rcp_f32_e32 v218, v218
	v_rcp_f32_e32 v219, v219
	v_rcp_f32_e32 v220, v220
	v_pk_mul_f32 v[26:27], v[26:27], v[216:217]
	v_rcp_f32_e32 v221, v221
	v_pk_mul_f32 v[26:27], v[18:19], v[26:27]
	v_rcp_f32_e32 v222, v222
	v_pk_mul_f32 v[28:29], v[28:29], v[218:219]
	v_rcp_f32_e32 v223, v223
	v_pk_mul_f32 v[20:21], v[20:21], v[28:29]
	v_pk_mul_f32 v[30:31], v[30:31], v[220:221]
	v_pk_mul_f32 v[22:23], v[22:23], v[30:31]
	v_pk_mul_f32 v[32:33], v[32:33], v[222:223]
	v_pk_mul_f32 v[24:25], v[24:25], v[32:33]
	v_cvt_pk_bf16_f32 v18, v22, v23
	v_cvt_pk_bf16_f32 v19, v24, v25
	v_cvt_pk_bf16_f32 v21, v20, v21
	v_cvt_pk_bf16_f32 v20, v26, v27
	ds_write_b128 v160, v[18:21]
	ds_read_b128 v[18:21], v161
	v_add_co_u32_e32 v22, vcc, s62, v114
	s_nop 1
	v_addc_co_u32_e32 v23, vcc, 0, v115, vcc
	s_waitcnt lgkmcnt(0)
	global_store_dwordx4 v[22:23], v[18:21], off
	s_nop 1
	v_add_co_u32_e32 v20, vcc, 0xf2000, v114
	v_fmamk_f32 v18, v207, 0x3a800000, v159
	v_rsq_f32_e32 v18, v18
	s_nop 0
	v_pk_mul_f32 v[12:13], v[12:13], v[18:19] op_sel_hi:[1,0]
	v_pk_mul_f32 v[16:17], v[16:17], v[18:19] op_sel_hi:[1,0]
	v_pk_mul_f32 v[14:15], v[14:15], v[18:19] op_sel_hi:[1,0]
	v_pk_mul_f32 v[10:11], v[10:11], v[18:19] op_sel_hi:[1,0]
	v_pk_mul_f32 v[8:9], v[8:9], v[18:19] op_sel_hi:[1,0]
	v_pk_mul_f32 v[6:7], v[6:7], v[18:19] op_sel_hi:[1,0]
	v_pk_mul_f32 v[4:5], v[4:5], v[18:19] op_sel_hi:[1,0]
	v_pk_mul_f32 v[2:3], v[2:3], v[18:19] op_sel_hi:[1,0]
	v_pk_mul_f32 v[216:217], v[10:11], v[212:213] op_sel_hi:[1,0]
	v_pk_mul_f32 v[218:219], v[12:13], v[212:213] op_sel_hi:[1,0]
	v_pk_mul_f32 v[220:221], v[14:15], v[212:213] op_sel_hi:[1,0]
	v_pk_mul_f32 v[222:223], v[16:17], v[212:213] op_sel_hi:[1,0]
	v_exp_f32_e32 v216, v216
	v_exp_f32_e32 v217, v217
	v_exp_f32_e32 v218, v218
	v_exp_f32_e32 v219, v219
	v_exp_f32_e32 v220, v220
	v_pk_add_f32 v[216:217], v[216:217], v[214:215] op_sel_hi:[1,0]
	v_exp_f32_e32 v221, v221
	v_pk_add_f32 v[218:219], v[218:219], v[214:215] op_sel_hi:[1,0]
	v_exp_f32_e32 v222, v222
	v_exp_f32_e32 v223, v223
	v_rcp_f32_e32 v216, v216
	v_pk_add_f32 v[220:221], v[220:221], v[214:215] op_sel_hi:[1,0]
	v_rcp_f32_e32 v217, v217
	v_pk_add_f32 v[222:223], v[222:223], v[214:215] op_sel_hi:[1,0]
	v_rcp_f32_e32 v218, v218
	v_rcp_f32_e32 v219, v219
	v_rcp_f32_e32 v220, v220
	v_pk_mul_f32 v[10:11], v[10:11], v[216:217]
	v_rcp_f32_e32 v221, v221
	v_pk_mul_f32 v[10:11], v[2:3], v[10:11]
	v_rcp_f32_e32 v222, v222
	v_pk_mul_f32 v[12:13], v[12:13], v[218:219]
	v_rcp_f32_e32 v223, v223
	v_pk_mul_f32 v[4:5], v[4:5], v[12:13]
	v_pk_mul_f32 v[14:15], v[14:15], v[220:221]
	v_pk_mul_f32 v[6:7], v[6:7], v[14:15]
	v_pk_mul_f32 v[16:17], v[16:17], v[222:223]
	v_pk_mul_f32 v[8:9], v[8:9], v[16:17]
	v_cvt_pk_bf16_f32 v2, v6, v7
	v_cvt_pk_bf16_f32 v3, v8, v9
	v_cvt_pk_bf16_f32 v5, v4, v5
	v_cvt_pk_bf16_f32 v4, v10, v11
	ds_write_b128 v162, v[2:5]
	ds_read_b128 v[2:5], v163
	v_addc_co_u32_e32 v21, vcc, 0, v115, vcc
	s_andn2_b64 vcc, exec, s[0:1]
	s_mov_b64 s[0:1], -1
	s_waitcnt lgkmcnt(0)
	global_store_dwordx4 v[20:21], v[2:5], off
	s_cbranch_vccnz .LBB0_873
	s_andn2_b64 vcc, exec, s[12:13]
	s_cbranch_vccnz .LBB0_872
	s_barrier
	s_branch .LBB0_872
